# combo11 = combo9 + GEMM K-loop heads aligned to 64-byte instruction-cache lines (code placement)
# speedup vs baseline: 1.0055x; 1.0055x over previous
;     __device__ __forceinline__ bool next(int i, Unit& u) const { if (i != 0 || c >= 8) return false; u.pm = c >> 2; u.pn = c; return true; }
; template <class Epi, class Sched, bool ALIGN_EPI = false, bool SP2 = false>
; __device__ __forceinline__ void gemm_phase(PG8_LAS unsigned char* lds, const Gemm g, const Sched& S, const Epi& E) {
;     ...
;         const bool has_next = S.next(ui + 1, nxt);
;         const char* nA = has_next ? (const char*)g.A + (size_t)nxt.pm * tstep : cA; const char* nB = has_next ? (const char*)g.Bt + (size_t)nxt.pn * tstep : cB;
;         for (int t = 0; t < nt; t += 2) {
;             const bool last = (t == nt - 2);
;             const char* a1 = cA + (size_t)(t + 1) * kstep;
;             const char* a2 = last ? nA : cA + (size_t)(t + 2) * kstep; const char* b2 = last ? nB : cB + (size_t)(t + 2) * kstep;
;             const char* a3 = a2 + kstep; const char* b3 = b2 + kstep;
;     ...
; #pragma unroll
;         for (int a = 0; a < 2; ++a)
; #pragma unroll
;             for (int b = 0; b < 2; ++b)
; #pragma unroll
;                 for (int m = 0; m < 4; ++m)
; #pragma unroll
;                     for (int n = 0; n < 2; ++n) acc[a][b][m][n] = (f32x4){0.f, 0.f, 0.f, 0.f};
;         cur = nxt; cA = nA; cB = nB; ++ui;
.LBB0_423:
	s_ashr_i32 s29, s28, 31
	s_lshl_b64 s[0:1], s[28:29], 20
	s_add_u32 s60, s88, s0
	s_addc_u32 s61, s89, s1
	s_and_b64 s[0:1], s[6:7], exec
	s_cselect_b32 s14, s61, s67
	s_cselect_b32 s15, s60, s66
	s_ashr_i32 s95, s94, 31
	s_lshl_b64 s[0:1], s[94:95], 20
	s_add_u32 s0, s21, s0
	s_addc_u32 s1, s22, s1
	s_and_b64 s[16:17], s[6:7], exec
	s_cselect_b32 s16, s1, s9
	s_cselect_b32 s17, s0, s8
	s_add_u32 s18, s8, 0x100
	s_addc_u32 s19, s9, 0
	s_add_u32 s8, s66, 0x80080
	v_mov_b32_e32 v0, 0
	s_addc_u32 s9, s67, 0
	s_mov_b32 s29, -2
	v_mov_b32_e32 v1, v0
	v_mov_b32_e32 v2, v0
	v_mov_b32_e32 v3, v0
	v_mov_b32_e32 v4, v0
	v_mov_b32_e32 v5, v0
	v_mov_b32_e32 v6, v0
	v_mov_b32_e32 v7, v0
	v_mov_b32_e32 v12, v0
	v_mov_b32_e32 v13, v0
	v_mov_b32_e32 v14, v0
	v_mov_b32_e32 v15, v0
	v_mov_b32_e32 v20, v0
	v_mov_b32_e32 v21, v0
	v_mov_b32_e32 v22, v0
	v_mov_b32_e32 v23, v0
	v_mov_b32_e32 v28, v0
	v_mov_b32_e32 v29, v0
	v_mov_b32_e32 v30, v0
	v_mov_b32_e32 v31, v0
	v_mov_b32_e32 v36, v0
	v_mov_b32_e32 v37, v0
	v_mov_b32_e32 v38, v0
	v_mov_b32_e32 v39, v0
	v_mov_b32_e32 v48, v0
	v_mov_b32_e32 v49, v0
	v_mov_b32_e32 v50, v0
	v_mov_b32_e32 v51, v0
	v_mov_b32_e32 v56, v0
	v_mov_b32_e32 v57, v0
	v_mov_b32_e32 v58, v0
	v_mov_b32_e32 v59, v0
	v_mov_b32_e32 v8, v0
	v_mov_b32_e32 v9, v0
	v_mov_b32_e32 v10, v0
	v_mov_b32_e32 v11, v0
	v_mov_b32_e32 v16, v0
	v_mov_b32_e32 v17, v0
	v_mov_b32_e32 v18, v0
	v_mov_b32_e32 v19, v0
	v_mov_b32_e32 v24, v0
	v_mov_b32_e32 v25, v0
	v_mov_b32_e32 v26, v0
	v_mov_b32_e32 v27, v0
	v_mov_b32_e32 v32, v0
	v_mov_b32_e32 v33, v0
	v_mov_b32_e32 v34, v0
	v_mov_b32_e32 v35, v0
	v_mov_b32_e32 v44, v0
	v_mov_b32_e32 v45, v0
	v_mov_b32_e32 v46, v0
	v_mov_b32_e32 v47, v0
	v_mov_b32_e32 v52, v0
	v_mov_b32_e32 v53, v0
	v_mov_b32_e32 v54, v0
	v_mov_b32_e32 v55, v0
	v_mov_b32_e32 v60, v0
	v_mov_b32_e32 v61, v0
	v_mov_b32_e32 v62, v0
	v_mov_b32_e32 v63, v0
	v_mov_b32_e32 v64, v0
	v_mov_b32_e32 v65, v0
	v_mov_b32_e32 v66, v0
	v_mov_b32_e32 v67, v0
	v_mov_b32_e32 v68, v0
	v_mov_b32_e32 v69, v0
	v_mov_b32_e32 v70, v0
	v_mov_b32_e32 v71, v0
	v_mov_b32_e32 v72, v0
	v_mov_b32_e32 v73, v0
	v_mov_b32_e32 v74, v0
	v_mov_b32_e32 v75, v0
	v_mov_b32_e32 v80, v0
	v_mov_b32_e32 v81, v0
	v_mov_b32_e32 v82, v0
	v_mov_b32_e32 v83, v0
	v_mov_b32_e32 v88, v0
	v_mov_b32_e32 v89, v0
	v_mov_b32_e32 v90, v0
	v_mov_b32_e32 v91, v0
	v_mov_b32_e32 v96, v0
	v_mov_b32_e32 v97, v0
	v_mov_b32_e32 v98, v0
	v_mov_b32_e32 v99, v0
	v_mov_b32_e32 v104, v0
	v_mov_b32_e32 v105, v0
	v_mov_b32_e32 v106, v0
	v_mov_b32_e32 v107, v0
	v_mov_b32_e32 v112, v0
	v_mov_b32_e32 v113, v0
	v_mov_b32_e32 v114, v0
	v_mov_b32_e32 v115, v0
	v_mov_b32_e32 v120, v0
	v_mov_b32_e32 v121, v0
	v_mov_b32_e32 v122, v0
	v_mov_b32_e32 v123, v0
	v_mov_b32_e32 v76, v0
	v_mov_b32_e32 v77, v0
	v_mov_b32_e32 v78, v0
	v_mov_b32_e32 v79, v0
	v_mov_b32_e32 v84, v0
	v_mov_b32_e32 v85, v0
	v_mov_b32_e32 v86, v0
	v_mov_b32_e32 v87, v0
	v_mov_b32_e32 v92, v0
	v_mov_b32_e32 v93, v0
	v_mov_b32_e32 v94, v0
	v_mov_b32_e32 v95, v0
	v_mov_b32_e32 v100, v0
	v_mov_b32_e32 v101, v0
	v_mov_b32_e32 v102, v0
	v_mov_b32_e32 v103, v0
	v_mov_b32_e32 v108, v0
	v_mov_b32_e32 v109, v0
	v_mov_b32_e32 v110, v0
	v_mov_b32_e32 v111, v0
	v_mov_b32_e32 v116, v0
	v_mov_b32_e32 v117, v0
	v_mov_b32_e32 v118, v0
	v_mov_b32_e32 v119, v0
	v_mov_b32_e32 v124, v0
	v_mov_b32_e32 v125, v0
	v_mov_b32_e32 v126, v0
	v_mov_b32_e32 v127, v0
	v_mov_b32_e32 v130, v0
	v_mov_b32_e32 v131, v0
	v_mov_b32_e32 v132, v0
	v_mov_b32_e32 v133, v0
	.p2align	6

;     __device__ __forceinline__ bool next(int i, Unit& u) const { if (i != 0 || c >= 8) return false; u.pm = c >> 2; u.pn = c; return true; }
; template <class Epi, class Sched, bool ALIGN_EPI = false, bool SP2 = false>
; __device__ __forceinline__ void gemm_phase(PG8_LAS unsigned char* lds, const Gemm g, const Sched& S, const Epi& E) {
;     ...
;         const bool has_next = S.next(ui + 1, nxt);
;         const char* nA = has_next ? (const char*)g.A + (size_t)nxt.pm * tstep : cA; const char* nB = has_next ? (const char*)g.Bt + (size_t)nxt.pn * tstep : cB;
;         for (int t = 0; t < nt; t += 2) {
;             const bool last = (t == nt - 2);
;             const char* a1 = cA + (size_t)(t + 1) * kstep;
;             const char* a2 = last ? nA : cA + (size_t)(t + 2) * kstep; const char* b2 = last ? nB : cB + (size_t)(t + 2) * kstep;
;             const char* a3 = a2 + kstep; const char* b3 = b2 + kstep;
;     ...
; #pragma unroll
;         for (int a = 0; a < 2; ++a)
; #pragma unroll
;             for (int b = 0; b < 2; ++b)
; #pragma unroll
;                 for (int m = 0; m < 4; ++m)
; #pragma unroll
;                     for (int n = 0; n < 2; ++n) acc[a][b][m][n] = (f32x4){0.f, 0.f, 0.f, 0.f};
;         cur = nxt; cA = nA; cB = nB; ++ui;
.LBB0_457:
	s_add_u32 s13, s66, 0x100
	s_addc_u32 s91, s67, 0
	s_add_u32 s10, s96, 0x80
	v_mov_b32_e32 v0, 0
	s_addc_u32 s11, s97, 0
	s_mov_b32 s66, 0
	v_mov_b32_e32 v1, v0
	v_mov_b32_e32 v2, v0
	v_mov_b32_e32 v3, v0
	v_mov_b32_e32 v4, v0
	v_mov_b32_e32 v5, v0
	v_mov_b32_e32 v6, v0
	v_mov_b32_e32 v7, v0
	v_mov_b32_e32 v16, v0
	v_mov_b32_e32 v17, v0
	v_mov_b32_e32 v18, v0
	v_mov_b32_e32 v19, v0
	v_mov_b32_e32 v20, v0
	v_mov_b32_e32 v21, v0
	v_mov_b32_e32 v22, v0
	v_mov_b32_e32 v23, v0
	v_mov_b32_e32 v32, v0
	v_mov_b32_e32 v33, v0
	v_mov_b32_e32 v34, v0
	v_mov_b32_e32 v35, v0
	v_mov_b32_e32 v36, v0
	v_mov_b32_e32 v37, v0
	v_mov_b32_e32 v38, v0
	v_mov_b32_e32 v39, v0
	v_mov_b32_e32 v52, v0
	v_mov_b32_e32 v53, v0
	v_mov_b32_e32 v54, v0
	v_mov_b32_e32 v55, v0
	v_mov_b32_e32 v56, v0
	v_mov_b32_e32 v57, v0
	v_mov_b32_e32 v58, v0
	v_mov_b32_e32 v59, v0
	v_mov_b32_e32 v8, v0
	v_mov_b32_e32 v9, v0
	v_mov_b32_e32 v10, v0
	v_mov_b32_e32 v11, v0
	v_mov_b32_e32 v12, v0
	v_mov_b32_e32 v13, v0
	v_mov_b32_e32 v14, v0
	v_mov_b32_e32 v15, v0
	v_mov_b32_e32 v24, v0
	v_mov_b32_e32 v25, v0
	v_mov_b32_e32 v26, v0
	v_mov_b32_e32 v27, v0
	v_mov_b32_e32 v28, v0
	v_mov_b32_e32 v29, v0
	v_mov_b32_e32 v30, v0
	v_mov_b32_e32 v31, v0
	v_mov_b32_e32 v40, v0
	v_mov_b32_e32 v41, v0
	v_mov_b32_e32 v42, v0
	v_mov_b32_e32 v43, v0
	v_mov_b32_e32 v44, v0
	v_mov_b32_e32 v45, v0
	v_mov_b32_e32 v46, v0
	v_mov_b32_e32 v47, v0
	v_mov_b32_e32 v64, v0
	v_mov_b32_e32 v65, v0
	v_mov_b32_e32 v66, v0
	v_mov_b32_e32 v67, v0
	v_mov_b32_e32 v68, v0
	v_mov_b32_e32 v69, v0
	v_mov_b32_e32 v70, v0
	v_mov_b32_e32 v71, v0
	v_mov_b32_e32 v76, v0
	v_mov_b32_e32 v77, v0
	v_mov_b32_e32 v78, v0
	v_mov_b32_e32 v79, v0
	v_mov_b32_e32 v80, v0
	v_mov_b32_e32 v81, v0
	v_mov_b32_e32 v82, v0
	v_mov_b32_e32 v83, v0
	v_mov_b32_e32 v100, v0
	v_mov_b32_e32 v101, v0
	v_mov_b32_e32 v102, v0
	v_mov_b32_e32 v103, v0
	v_mov_b32_e32 v104, v0
	v_mov_b32_e32 v105, v0
	v_mov_b32_e32 v106, v0
	v_mov_b32_e32 v107, v0
	v_mov_b32_e32 v124, v0
	v_mov_b32_e32 v125, v0
	v_mov_b32_e32 v126, v0
	v_mov_b32_e32 v127, v0
	v_mov_b32_e32 v130, v0
	v_mov_b32_e32 v131, v0
	v_mov_b32_e32 v132, v0
	v_mov_b32_e32 v133, v0
	v_mov_b32_e32 v154, v0
	v_mov_b32_e32 v155, v0
	v_mov_b32_e32 v156, v0
	v_mov_b32_e32 v157, v0
	v_mov_b32_e32 v158, v0
	v_mov_b32_e32 v159, v0
	v_mov_b32_e32 v160, v0
	v_mov_b32_e32 v161, v0
	v_mov_b32_e32 v88, v0
	v_mov_b32_e32 v89, v0
	v_mov_b32_e32 v90, v0
	v_mov_b32_e32 v91, v0
	v_mov_b32_e32 v92, v0
	v_mov_b32_e32 v93, v0
	v_mov_b32_e32 v94, v0
	v_mov_b32_e32 v95, v0
	v_mov_b32_e32 v112, v0
	v_mov_b32_e32 v113, v0
	v_mov_b32_e32 v114, v0
	v_mov_b32_e32 v115, v0
	v_mov_b32_e32 v116, v0
	v_mov_b32_e32 v117, v0
	v_mov_b32_e32 v118, v0
	v_mov_b32_e32 v119, v0
	v_mov_b32_e32 v138, v0
	v_mov_b32_e32 v139, v0
	v_mov_b32_e32 v140, v0
	v_mov_b32_e32 v141, v0
	v_mov_b32_e32 v142, v0
	v_mov_b32_e32 v143, v0
	v_mov_b32_e32 v144, v0
	v_mov_b32_e32 v145, v0
	v_mov_b32_e32 v162, v0
	v_mov_b32_e32 v163, v0
	v_mov_b32_e32 v164, v0
	v_mov_b32_e32 v165, v0
	v_mov_b32_e32 v166, v0
	v_mov_b32_e32 v167, v0
	v_mov_b32_e32 v168, v0
	v_mov_b32_e32 v169, v0
	.p2align	6

;     __device__ __forceinline__ bool next(int i, Unit& u) const { if (i != 0 || c >= 8) return false; u.pm = c >> 2; u.pn = c; return true; }
; template <class Epi, class Sched, bool ALIGN_EPI = false, bool SP2 = false>
; __device__ __forceinline__ void gemm_phase(PG8_LAS unsigned char* lds, const Gemm g, const Sched& S, const Epi& E) {
;     ...
;         const bool has_next = S.next(ui + 1, nxt);
;         const char* nA = has_next ? (const char*)g.A + (size_t)nxt.pm * tstep : cA; const char* nB = has_next ? (const char*)g.Bt + (size_t)nxt.pn * tstep : cB;
;         for (int t = 0; t < nt; t += 2) {
;             const bool last = (t == nt - 2);
;             const char* a1 = cA + (size_t)(t + 1) * kstep;
;             const char* a2 = last ? nA : cA + (size_t)(t + 2) * kstep; const char* b2 = last ? nB : cB + (size_t)(t + 2) * kstep;
;             const char* a3 = a2 + kstep; const char* b3 = b2 + kstep;
;     ...
; #pragma unroll
;         for (int a = 0; a < 2; ++a)
; #pragma unroll
;             for (int b = 0; b < 2; ++b)
; #pragma unroll
;                 for (int m = 0; m < 4; ++m)
; #pragma unroll
;                     for (int n = 0; n < 2; ++n) acc[a][b][m][n] = (f32x4){0.f, 0.f, 0.f, 0.f};
;         cur = nxt; cA = nA; cB = nB; ++ui;
.LBB0_589:
	s_ashr_i32 s65, s64, 31
	s_lshl_b64 s[26:27], s[64:65], 20
	s_add_u32 s70, s88, s26
	s_addc_u32 s71, s89, s27
	s_and_b64 s[26:27], s[6:7], exec
	s_cselect_b32 s14, s71, s9
	s_cselect_b32 s26, s70, s8
	s_ashr_i32 s31, s30, 31
	s_lshl_b64 s[28:29], s[30:31], 20
	s_add_u32 s92, s17, s28
	s_addc_u32 s93, s18, s29
	s_and_b64 s[28:29], s[6:7], exec
	s_cselect_b32 s27, s93, s1
	s_cselect_b32 s31, s92, s0
	s_add_u32 s34, s0, 0x100
	s_addc_u32 s35, s1, 0
	s_add_u32 s0, s8, 0x80080
	v_mov_b32_e32 v0, 0
	s_addc_u32 s1, s9, 0
	s_mov_b32 s60, -2
	v_mov_b32_e32 v1, v0
	v_mov_b32_e32 v2, v0
	v_mov_b32_e32 v3, v0
	v_mov_b32_e32 v8, v0
	v_mov_b32_e32 v9, v0
	v_mov_b32_e32 v10, v0
	v_mov_b32_e32 v11, v0
	v_mov_b32_e32 v16, v0
	v_mov_b32_e32 v17, v0
	v_mov_b32_e32 v18, v0
	v_mov_b32_e32 v19, v0
	v_mov_b32_e32 v24, v0
	v_mov_b32_e32 v25, v0
	v_mov_b32_e32 v26, v0
	v_mov_b32_e32 v27, v0
	v_mov_b32_e32 v32, v0
	v_mov_b32_e32 v33, v0
	v_mov_b32_e32 v34, v0
	v_mov_b32_e32 v35, v0
	v_mov_b32_e32 v40, v0
	v_mov_b32_e32 v41, v0
	v_mov_b32_e32 v42, v0
	v_mov_b32_e32 v43, v0
	v_mov_b32_e32 v48, v0
	v_mov_b32_e32 v49, v0
	v_mov_b32_e32 v50, v0
	v_mov_b32_e32 v51, v0
	v_mov_b32_e32 v60, v0
	v_mov_b32_e32 v61, v0
	v_mov_b32_e32 v62, v0
	v_mov_b32_e32 v63, v0
	v_mov_b32_e32 v4, v0
	v_mov_b32_e32 v5, v0
	v_mov_b32_e32 v6, v0
	v_mov_b32_e32 v7, v0
	v_mov_b32_e32 v12, v0
	v_mov_b32_e32 v13, v0
	v_mov_b32_e32 v14, v0
	v_mov_b32_e32 v15, v0
	v_mov_b32_e32 v20, v0
	v_mov_b32_e32 v21, v0
	v_mov_b32_e32 v22, v0
	v_mov_b32_e32 v23, v0
	v_mov_b32_e32 v28, v0
	v_mov_b32_e32 v29, v0
	v_mov_b32_e32 v30, v0
	v_mov_b32_e32 v31, v0
	v_mov_b32_e32 v36, v0
	v_mov_b32_e32 v37, v0
	v_mov_b32_e32 v38, v0
	v_mov_b32_e32 v39, v0
	v_mov_b32_e32 v44, v0
	v_mov_b32_e32 v45, v0
	v_mov_b32_e32 v46, v0
	v_mov_b32_e32 v47, v0
	v_mov_b32_e32 v52, v0
	v_mov_b32_e32 v53, v0
	v_mov_b32_e32 v54, v0
	v_mov_b32_e32 v55, v0
	v_mov_b32_e32 v64, v0
	v_mov_b32_e32 v65, v0
	v_mov_b32_e32 v66, v0
	v_mov_b32_e32 v67, v0
	v_mov_b32_e32 v68, v0
	v_mov_b32_e32 v69, v0
	v_mov_b32_e32 v70, v0
	v_mov_b32_e32 v71, v0
	v_mov_b32_e32 v76, v0
	v_mov_b32_e32 v77, v0
	v_mov_b32_e32 v78, v0
	v_mov_b32_e32 v79, v0
	v_mov_b32_e32 v84, v0
	v_mov_b32_e32 v85, v0
	v_mov_b32_e32 v86, v0
	v_mov_b32_e32 v87, v0
	v_mov_b32_e32 v92, v0
	v_mov_b32_e32 v93, v0
	v_mov_b32_e32 v94, v0
	v_mov_b32_e32 v95, v0
	v_mov_b32_e32 v100, v0
	v_mov_b32_e32 v101, v0
	v_mov_b32_e32 v102, v0
	v_mov_b32_e32 v103, v0
	v_mov_b32_e32 v112, v0
	v_mov_b32_e32 v113, v0
	v_mov_b32_e32 v114, v0
	v_mov_b32_e32 v115, v0
	v_mov_b32_e32 v120, v0
	v_mov_b32_e32 v121, v0
	v_mov_b32_e32 v122, v0
	v_mov_b32_e32 v123, v0
	v_mov_b32_e32 v130, v0
	v_mov_b32_e32 v131, v0
	v_mov_b32_e32 v132, v0
	v_mov_b32_e32 v133, v0
	v_mov_b32_e32 v72, v0
	v_mov_b32_e32 v73, v0
	v_mov_b32_e32 v74, v0
	v_mov_b32_e32 v75, v0
	v_mov_b32_e32 v80, v0
	v_mov_b32_e32 v81, v0
	v_mov_b32_e32 v82, v0
	v_mov_b32_e32 v83, v0
	v_mov_b32_e32 v88, v0
	v_mov_b32_e32 v89, v0
	v_mov_b32_e32 v90, v0
	v_mov_b32_e32 v91, v0
	v_mov_b32_e32 v96, v0
	v_mov_b32_e32 v97, v0
	v_mov_b32_e32 v98, v0
	v_mov_b32_e32 v99, v0
	v_mov_b32_e32 v104, v0
	v_mov_b32_e32 v105, v0
	v_mov_b32_e32 v106, v0
	v_mov_b32_e32 v107, v0
	v_mov_b32_e32 v116, v0
	v_mov_b32_e32 v117, v0
	v_mov_b32_e32 v118, v0
	v_mov_b32_e32 v119, v0
	v_mov_b32_e32 v124, v0
	v_mov_b32_e32 v125, v0
	v_mov_b32_e32 v126, v0
	v_mov_b32_e32 v127, v0
	v_mov_b32_e32 v134, v0
	v_mov_b32_e32 v135, v0
	v_mov_b32_e32 v136, v0
	v_mov_b32_e32 v137, v0
	.p2align	6
